# GEMM1 runs 44 column tiles (22 exact rounds); the 16 mLSTM gate columns computed by a per-wave MFMA block after the GEMM; scan Q loads issued earlier
# speedup vs baseline: 1.0009x; 1.0009x over previous
; #define PG8_STAGE(bufoff, gbase, voff) do { _Pragma("unroll") for (int _i = 0; _i < 2; ++_i) \
;         __builtin_amdgcn_global_load_lds((const unsigned*)((const char*)(gbase) + (voff)[_i]), (PG8_LAS unsigned*)(lds + (bufoff) + ldsw + _i * 8192), 16, 0, 0); } while (0)
; #define PG8_WAIT_V(n) asm volatile("s_waitcnt vmcnt(" #n ")" ::: "memory")
; template <class Epi, class Sched, bool ALIGN_EPI = false, bool SP2 = false>
; __device__ __forceinline__ void gemm_phase(PG8_LAS unsigned char* lds, const Gemm g, const Sched& S, const Epi& E) {
;     const int tid = threadIdx.x, wid = __builtin_amdgcn_readfirstlane(tid >> 6), lane = tid & 63, wr = wid >> 2, wc = wid & 3, fr = lane & 15, fq = lane >> 4;
;     const int K = g.K, nt = K / BK;
;     unsigned voffA[2], voffB[2];
; #pragma unroll
;     for (int i = 0; i < 2; ++i) { int R, C; stage_rc(tid * 16 + i * 8192, R, C); const int Rb = Epi::PERM ? ((R & ~31) + perm32(R & 31)) : R;
;         voffA[i] = (unsigned)(R * K + C) * 2u; voffB[i] = (unsigned)(Rb * K + C) * 2u; }
;     const size_t kstep = (size_t)(BK * 2);
;     const size_t hstep = (size_t)HALF * K * 2;
;     const size_t tstep = 2 * hstep;
;     const unsigned ldsw = (unsigned)wid * 1024u;
;     const int aoff = lds_byte(wr * 64 + fr, fq * 8), boff = lds_byte(wc * 32 + fr, fq * 8);
;     ...
;     Unit cur, nxt; int ui = 0;
;     if (!S.next(0, cur)) return;
;     f32x4 acc[2][2][4][2];
; #pragma unroll
;     for (int a = 0; a < 2; ++a)
; #pragma unroll
;         for (int b = 0; b < 2; ++b)
; #pragma unroll
;             for (int m = 0; m < 4; ++m)
; #pragma unroll
;                 for (int n = 0; n < 2; ++n) acc[a][b][m][n] = (f32x4){0.f, 0.f, 0.f, 0.f};
;     bf16x8 At[4][2], B0[2][2], B1[2][2];
;     const char* cA = (const char*)(cur.seg ? g.A2 : g.A) + (size_t)cur.pm * tstep; const char* cB = (const char*)(cur.seg ? g.Bt2 : g.Bt) + (size_t)cur.pn * tstep;
;     S.a_ready(cur);
;     if constexpr (SP2) {
;         PG8_STAGE(PG8_SB(0, 0), cB, voffB); PG8_STAGE(PG8_SB(0, 1), cB + hstep, voffB); PG8_STAGE(PG8_SA(0, 0), cA, voffA); PG8_STAGE(PG8_SA(0, 1), cA + hstep, voffA);
;         if (wr == 1) PG8_BAR;
;         PG8_WAIT_V(2); PG8_BAR;
;         PG8_STAGE(PG8_SB(1, 0), cB + kstep, voffB); PG8_STAGE(PG8_SA(1, 0), cA + kstep, voffA); PG8_STAGE(PG8_SB(1, 1), cB + hstep + kstep, voffB);
;         PG8_WAIT_V(6); PG8_BAR;
.LBB0_121:
	v_readlane_b32 s0, v246, 12
	v_readlane_b32 s1, v246, 13
	s_cmp_lt_i32 s0, 2
	v_readlane_b32 s2, v246, 14
	v_readlane_b32 s3, v246, 15
	s_cselect_b64 s[0:1], -1, 0
	s_and_b64 s[2:3], s[0:1], s[4:5]
	s_andn2_b64 vcc, exec, s[2:3]
	s_cbranch_vccnz .LBB0_158
	v_readlane_b32 s2, v246, 0
	s_cmpk_gt_i32 s2, 0x15ff
	v_readfirstlane_b32 s7, v144
	v_readlane_b32 s3, v246, 1
	s_cbranch_scc1 .LBB0_158
	v_lshrrev_b32_e32 v0, 5, v144
	v_lshrrev_b32_e32 v2, 1, v144
	v_readlane_b32 s2, v246, 10
	v_and_b32_e32 v0, 4, v0
	v_bfe_u32 v1, v144, 2, 2
	v_and_b32_e32 v2, 24, v2
	v_readlane_b32 s3, v246, 11
	s_add_u32 s35, s2, 0x8800000
	v_or3_b32 v0, v0, v1, v2
	v_lshlrev_b32_e32 v1, 4, v144
	s_addc_u32 s54, s3, 0
	s_waitcnt vmcnt(1)
	v_add_u32_e32 v8, 0x2000, v1
	s_add_u32 s55, s2, 0x100000
	v_lshrrev_b32_e32 v2, 7, v8
	s_movk_i32 s2, 0xe0
	v_and_b32_e32 v4, 32, v144
	v_and_or_b32 v3, v2, s2, v0
	v_bitop3_b32 v9, v1, v4, 48 bitop3:0x6c
	v_and_b32_e32 v10, 64, v144
	v_bfe_u32 v11, v144, 2, 4
	s_movk_i32 s2, 0xf0
	v_or_b32_e32 v1, v9, v10
	v_and_or_b32 v2, v2, s2, v11
	v_lshl_or_b32 v130, v2, 12, v1
	v_lshrrev_b32_e32 v2, 3, v144
	s_movk_i32 s2, 0x60
	v_and_or_b32 v0, v2, s2, v0
	s_movk_i32 s2, 0x70
	s_addc_u32 s56, s3, 0
	v_lshl_or_b32 v132, v0, 12, v1
	v_and_or_b32 v0, v2, s2, v11
	v_readlane_b32 s2, v246, 0
	s_ashr_i32 s58, s2, 31
	s_mov_b32 s4, s2
	s_lshr_b32 s2, s58, 29
	v_readlane_b32 s3, v246, 1
	s_add_i32 s2, s4, s2
	s_lshr_b32 s12, s7, 6
	s_ashr_i32 s3, s2, 3
	s_and_b32 s2, s2, -8
	s_lshr_b32 s14, s7, 8
	s_lshl_b32 s57, s12, 10
	s_sub_i32 s2, s4, s2
	s_cmp_lt_i32 s2, 0
	s_movk_i32 s59, 0x2c1
	s_cselect_b32 s4, s59, 0x2c0
	s_mul_i32 s2, s2, s4
	s_add_i32 s2, s2, s3
	s_mul_hi_i32 s3, s2, 0xba2e8ba4
	s_add_i32 s3, s3, s2
	s_lshr_b32 s4, s3, 31
	s_ashr_i32 s3, s3, 8
	s_add_i32 s3, s3, s4
	s_lshl_b32 s4, s3, 3
	s_mulk_i32 s3, 0x160
	s_sub_i32 s2, s2, s3
	s_sext_i32_i16 s3, s2
	s_bfe_u32 s3, s3, 0x3001c
	s_add_i32 s3, s2, s3
	s_sext_i32_i16 s5, s3
	s_and_b32 s3, s3, 0xfff8
	s_sub_i32 s2, s2, s3
	s_sext_i32_i16 s2, s2
	s_lshr_b32 s6, s5, 3
	s_add_i32 s46, s4, s2
	s_ashr_i32 s47, s46, 31
	s_bfe_i64 s[4:5], s[6:7], 0x100000
	s_lshl_b64 s[2:3], s[46:47], 20
	s_lshl_b64 s[4:5], s[4:5], 20
	s_add_u32 s50, s55, s4
	s_addc_u32 s51, s56, s5
	s_add_i32 s60, s57, 0
	s_add_i32 m0, s60, 0x10000
	v_lshl_or_b32 v128, v3, 12, v1
	global_load_lds_dwordx4 v132, s[50:51]
	s_add_i32 m0, s60, 0x12000
	s_add_u32 s4, s50, 0x80000
	global_load_lds_dwordx4 v128, s[50:51]
	s_addc_u32 s5, s51, 0
	s_add_i32 m0, s60, 0x14000
	v_lshl_or_b32 v134, v0, 12, v1
	global_load_lds_dwordx4 v132, s[4:5]
	s_add_i32 m0, s60, 0x16000
	s_add_u32 s48, s35, s2
	s_addc_u32 s49, s54, s3
	s_add_i32 s61, s60, 0x2000
	global_load_lds_dwordx4 v128, s[4:5]
	s_mov_b32 m0, s60
	s_add_u32 s2, s48, 0x80000
	global_load_lds_dwordx4 v134, s[48:49]
	s_mov_b32 m0, s61
	s_addc_u32 s3, s49, 0
	s_add_i32 s62, s60, 0x4000
	global_load_lds_dwordx4 v130, s[48:49]
	s_mov_b32 m0, s62
	s_add_i32 s63, s60, 0x6000
	global_load_lds_dwordx4 v134, s[2:3]
	s_mov_b32 m0, s63
	v_mov_b32_e32 v133, 0
	global_load_lds_dwordx4 v130, s[2:3]
	v_mov_b32_e32 v129, v133
	v_mov_b32_e32 v135, v133
	v_mov_b32_e32 v131, v133
	s_cmp_eq_u32 s14, 1
	s_mov_b32 s64, 0
	v_lshl_add_u64 v[6:7], s[50:51], 0, v[132:133]
	v_lshl_add_u64 v[4:5], s[50:51], 0, v[128:129]
	v_lshl_add_u64 v[0:1], s[48:49], 0, v[134:135]
	s_cselect_b64 s[2:3], -1, 0
	s_cmp_lg_u32 s14, 1
	v_lshl_add_u64 v[2:3], s[48:49], 0, v[130:131]
	s_cbranch_scc1 .LBB0_125
	s_barrier
.LBB0_125:
	v_readlane_b32 s38, v246, 10
	v_readlane_b32 s39, v246, 11
	s_add_u32 s4, s38, 0x10800000
	s_addc_u32 s5, s39, 0
	s_add_u32 s8, s38, 0x1c800000
	s_addc_u32 s9, s39, 0
	s_add_u32 s10, s38, 0x24800000
	s_addc_u32 s11, s39, 0
	s_and_b32 s33, s12, 3
	s_mov_b64 s[12:13], 0x80
	s_add_i32 m0, s60, 0x18000
	v_lshl_add_u64 v[6:7], v[6:7], 0, s[12:13]
	s_lshl_b32 s15, s14, 13
	s_lshl_b32 s36, s33, 12
	s_waitcnt vmcnt(2)
	s_barrier
	global_load_lds_dwordx4 v[6:7], off
	v_lshl_add_u64 v[4:5], v[4:5], 0, s[12:13]
	s_add_i32 m0, s60, 0x1a000
	s_add_i32 s65, s60, 0x8000
	s_add_i32 s66, s60, 0xa000
	global_load_lds_dwordx4 v[4:5], off
	v_lshl_add_u64 v[0:1], v[0:1], 0, s[12:13]
	s_mov_b32 m0, s65
	s_add_u32 s18, s50, 0x80080
	global_load_lds_dwordx4 v[0:1], off
	v_lshl_add_u64 v[0:1], v[2:3], 0, s[12:13]
	s_mov_b32 m0, s66
	s_addc_u32 s19, s51, 0
	global_load_lds_dwordx4 v[0:1], off
	s_add_i32 m0, s60, 0x1c000
	v_lshl_add_u64 v[0:1], s[18:19], 0, v[132:133]
	global_load_lds_dwordx4 v[0:1], off
	v_lshl_add_u64 v[0:1], s[18:19], 0, v[128:129]
	s_add_i32 m0, s60, 0x1e000
	v_lshlrev_b32_e32 v4, 2, v144
	global_load_lds_dwordx4 v[0:1], off
	v_lshrrev_b32_e32 v0, 4, v144
	v_and_b32_e32 v0, 3, v0
	v_and_b32_e32 v1, 15, v144
	v_lshlrev_b32_e32 v3, 4, v0
	v_lshl_or_b32 v145, s14, 6, v1
	v_lshl_or_b32 v1, v1, 6, v3
	v_and_b32_e32 v4, 32, v4
	s_sext_i32_i16 s70, s6
	v_bitop3_b32 v5, v1, s15, v4 bitop3:0xde
	v_lshlrev_b32_e32 v1, 6, v144
	s_movk_i32 s6, 0x3c0
	s_cmpk_lt_u32 s7, 0x100
	v_and_or_b32 v1, v1, s6, v3
	s_cselect_b64 s[14:15], -1, 0
	s_cmp_eq_u32 s33, 0
	v_lshlrev_b32_e32 v2, 3, v0
	v_bitop3_b32 v154, s36, v1, v4 bitop3:0xf6
	s_cselect_b64 s[6:7], -1, 0
	v_cmp_gt_u32_e32 vcc, 2, v0
	v_lshlrev_b32_e32 v0, 5, v0
	v_mov_b32_e32 v1, v133
	s_and_b64 s[18:19], s[6:7], vcc
	v_lshl_add_u64 v[0:1], s[38:39], 0, v[0:1]
	s_mov_b64 s[6:7], 0x7f00000
	v_lshl_add_u64 v[136:137], v[0:1], 0, s[6:7]
	v_lshlrev_b32_e32 v0, 9, v144
	v_and_b32_e32 v0, 0x70000, v0
	v_lshlrev_b32_e32 v1, 12, v11
	v_or3_b32 v0, v9, v0, v1
	v_add_u32_e32 v138, v0, v10
	v_lshlrev_b32_e32 v0, 5, v8
	s_waitcnt vmcnt(6)
	v_and_b32_e32 v0, 0xf0000, v0
	v_or3_b32 v0, v9, v0, v1
	s_add_i32 s68, 0, 0x10000
	s_add_i32 s69, 0, 0x14000
	v_lshl_or_b32 v155, s33, 5, v2
	s_ashr_i32 s67, s34, 31
	v_mov_b32_e32 v139, v133
	v_add_u32_e32 v140, v0, v10
	v_mov_b32_e32 v141, v133
	v_mov_b64_e32 v[142:143], 0x1600
	v_mov_b64_e32 v[146:147], 0x15ff
	v_add_u32_e32 v156, s68, v154
	v_add_u32_e32 v157, s69, v154
	v_add_u32_e32 v158, 0, v5
	v_mov_b32_e32 v160, 0x437f0000
	s_barrier
	s_branch .LBB0_128

;     __device__ bool next(int i, pg8::Unit& u) const { if (!base.next(i >> 1, u)) return false; u.seg = i & 1; return true; }
;     __host__ __device__ bool next(int i, Unit& u) const {
;         const long L = (long)i * G + c; if (L >= nwg) return false;
;         int wgid = (int)L; { const int q = nwg / NXCD, r = nwg % NXCD, xcd = wgid % NXCD, off = wgid / NXCD; wgid = (xcd < r ? xcd * (q + 1) : r * (q + 1) + (xcd - r) * q) + off; }
;         const int nig = WGM * nN, gid = wgid / nig, fm = gid * WGM, gsz = (nM - fm) < WGM ? (nM - fm) : WGM;
;         u.pm = fm + ((wgid % nig) % gsz); u.pn = (wgid % nig) / gsz; u.seg = 0; return true;
; template <class Epi, class Sched, bool ALIGN_EPI = false, bool SP2 = false>
; __device__ __forceinline__ void gemm_phase(PG8_LAS unsigned char* lds, const Gemm g, const Sched& S, const Epi& E) {
;     ...
;         const bool has_next = S.next(ui + 1, nxt);
;         const char* nA = has_next ? (const char*)(nxt.seg ? g.A2 : g.A) + (size_t)nxt.pm * tstep : cA; const char* nB = has_next ? (const char*)(nxt.seg ? g.Bt2 : g.Bt) + (size_t)nxt.pn * tstep : cB;
.LBB0_128:
	s_add_i32 s64, s64, 1
	s_mul_i32 s6, s64, s67
	s_mul_hi_u32 s7, s64, s34
	s_add_i32 s7, s7, s6
	s_mul_i32 s6, s64, s34
	v_readlane_b32 s36, v246, 0
	s_add_u32 s42, s6, s36
	s_addc_u32 s43, s7, s58
	v_cmp_gt_i64_e32 vcc, s[42:43], v[146:147]
	v_cmp_lt_i64_e64 s[6:7], s[42:43], v[142:143]
	v_readlane_b32 s37, v246, 1
	s_cbranch_vccnz .LBB0_130
	s_ashr_i32 s33, s42, 31
	s_lshr_b32 s33, s33, 29
	s_add_i32 s33, s42, s33
	s_ashr_i32 s36, s33, 3
	s_and_b32 s33, s33, -8
	s_sub_i32 s33, s42, s33
	s_cmp_lt_i32 s33, 0
	s_cselect_b32 s37, s59, 0x2c0
	s_mul_i32 s33, s33, s37
	s_add_i32 s33, s33, s36
	s_mul_hi_i32 s36, s33, 0xba2e8ba4
	s_add_i32 s36, s36, s33
	s_lshr_b32 s37, s36, 31
	s_ashr_i32 s36, s36, 8
	s_add_i32 s36, s36, s37
	s_lshl_b32 s37, s36, 3
	s_sub_i32 s38, 0x80, s37
	s_min_i32 s39, s38, 8
	s_abs_i32 s38, s39
	v_cvt_f32_u32_e32 v0, s38
	s_sub_i32 s41, 0, s38
	s_mulk_i32 s36, 0x160
	s_sub_i32 s33, s33, s36
	v_rcp_iflag_f32_e32 v0, v0
	s_abs_i32 s36, s33
	s_xor_b32 s40, s33, s39
	s_ashr_i32 s40, s40, 31
	v_mul_f32_e32 v0, 0x4f7ffffe, v0
	v_cvt_u32_f32_e32 v0, v0
	s_nop 0
	v_readfirstlane_b32 s42, v0
	s_mul_i32 s41, s41, s42
	s_mul_hi_u32 s41, s42, s41
	s_add_i32 s42, s42, s41
	s_mul_hi_u32 s41, s36, s42
	s_mul_i32 s42, s41, s38
	s_sub_i32 s36, s36, s42
	s_add_i32 s43, s41, 1
	s_sub_i32 s42, s36, s38
	s_cmp_ge_u32 s36, s38
	s_cselect_b32 s41, s43, s41
	s_cselect_b32 s36, s42, s36
	s_add_i32 s42, s41, 1
	s_cmp_ge_u32 s36, s38
	s_cselect_b32 s36, s42, s41
	s_xor_b32 s36, s36, s40
	s_sub_i32 s38, s36, s40
	s_mul_i32 s36, s38, s39
	s_sub_i32 s33, s33, s36
	s_add_i32 s40, s37, s33

;     __device__ __forceinline__ void operator()(const f32x4 (&acc)[2][2][4][2], const pg8::Unit& u, int wr, int wc, int fr, int fq) const {
;     ...
;         if (pn == 44) {
;             if (wc == 0 && fq < 2) {
; #pragma unroll
;                 for (int ai = 0; ai < 2; ++ai)
; #pragma unroll
;                     for (int m = 0; m < 4; ++m) { float* gp = gates + (size_t)(row0 + ai * 128 + m * 16) * 16 + 8 * fq;
;                         *(f32x4*)gp = acc[ai][0][m][0]; *(f32x4*)(gp + 4) = acc[ai][0][m][1]; }
;             }
;             return;
.LBB0_157:
	s_waitcnt vmcnt(0)
	s_barrier
	v_readlane_b32 s36, v246, 10
	v_readlane_b32 s37, v246, 11
	v_readlane_b32 s38, v246, 0
	v_readfirstlane_b32 s39, v144
	v_and_b32_e32 v0, 15, v144
	v_bfe_u32 v1, v144, 4, 2
	v_lshlrev_b32_e32 v2, 6, v0
	v_lshlrev_b32_e32 v0, 12, v0
	v_lshl_or_b32 v0, v1, 4, v0
	v_lshl_or_b32 v2, v1, 4, v2
	s_lshr_b32 s39, s39, 6
	s_lshl_b32 s38, s38, 3
	s_add_i32 s38, s38, s39
	s_lshl_b32 s40, s34, 3
	s_add_u32 s42, s36, 0x2d00000
	s_addc_u32 s43, s37, 0
.Lgate_loop:
	s_cmp_ge_u32 s38, 0x800
	s_cbranch_scc1 .Lgate_done
	s_lshl_b32 s44, s38, 16
	s_add_u32 s46, s36, s44
	s_addc_u32 s47, s37, 0
	s_add_u32 s46, s46, 0x8800000
	s_addc_u32 s47, s47, 0
	s_lshl_b32 s44, s38, 10
	s_add_u32 s48, s36, s44
	s_addc_u32 s49, s37, 0
	s_add_u32 s48, s48, 0x7f00000
	s_addc_u32 s49, s49, 0
	global_load_dwordx4 v[8:11], v0, s[46:47] offset:0
	global_load_dwordx4 v[40:43], v0, s[42:43] offset:0
	global_load_dwordx4 v[12:15], v0, s[46:47] offset:64
	global_load_dwordx4 v[44:47], v0, s[42:43] offset:64
	global_load_dwordx4 v[16:19], v0, s[46:47] offset:128
	global_load_dwordx4 v[48:51], v0, s[42:43] offset:128
	global_load_dwordx4 v[20:23], v0, s[46:47] offset:192
	global_load_dwordx4 v[52:55], v0, s[42:43] offset:192
	global_load_dwordx4 v[24:27], v0, s[46:47] offset:256
	global_load_dwordx4 v[56:59], v0, s[42:43] offset:256
	global_load_dwordx4 v[28:31], v0, s[46:47] offset:320
	global_load_dwordx4 v[60:63], v0, s[42:43] offset:320
	global_load_dwordx4 v[32:35], v0, s[46:47] offset:384
	global_load_dwordx4 v[64:67], v0, s[42:43] offset:384
	global_load_dwordx4 v[36:39], v0, s[46:47] offset:448
	global_load_dwordx4 v[68:71], v0, s[42:43] offset:448
	global_load_dwordx4 v[72:75], v0, s[46:47] offset:512
	global_load_dwordx4 v[104:107], v0, s[42:43] offset:512
	global_load_dwordx4 v[76:79], v0, s[46:47] offset:576
	global_load_dwordx4 v[108:111], v0, s[42:43] offset:576
	global_load_dwordx4 v[80:83], v0, s[46:47] offset:640
	global_load_dwordx4 v[112:115], v0, s[42:43] offset:640
	global_load_dwordx4 v[84:87], v0, s[46:47] offset:704
	global_load_dwordx4 v[116:119], v0, s[42:43] offset:704
	global_load_dwordx4 v[88:91], v0, s[46:47] offset:768
	global_load_dwordx4 v[120:123], v0, s[42:43] offset:768
	global_load_dwordx4 v[92:95], v0, s[46:47] offset:832
	global_load_dwordx4 v[124:127], v0, s[42:43] offset:832
	global_load_dwordx4 v[96:99], v0, s[46:47] offset:896
	global_load_dwordx4 v[128:131], v0, s[42:43] offset:896
	global_load_dwordx4 v[100:103], v0, s[46:47] offset:960
	global_load_dwordx4 v[132:135], v0, s[42:43] offset:960
	s_waitcnt vmcnt(30)
	v_mfma_f32_16x16x32_bf16 v[4:7], v[40:43], v[8:11], 0
	s_waitcnt vmcnt(28)
	v_mfma_f32_16x16x32_bf16 v[4:7], v[44:47], v[12:15], v[4:7]
	s_waitcnt vmcnt(26)
	v_mfma_f32_16x16x32_bf16 v[4:7], v[48:51], v[16:19], v[4:7]
	s_waitcnt vmcnt(24)
	v_mfma_f32_16x16x32_bf16 v[4:7], v[52:55], v[20:23], v[4:7]
	s_waitcnt vmcnt(22)
	v_mfma_f32_16x16x32_bf16 v[4:7], v[56:59], v[24:27], v[4:7]
	s_waitcnt vmcnt(20)
	v_mfma_f32_16x16x32_bf16 v[4:7], v[60:63], v[28:31], v[4:7]
	s_waitcnt vmcnt(18)
	v_mfma_f32_16x16x32_bf16 v[4:7], v[64:67], v[32:35], v[4:7]
	s_waitcnt vmcnt(16)
	v_mfma_f32_16x16x32_bf16 v[4:7], v[68:71], v[36:39], v[4:7]
	global_load_dwordx4 v[8:11], v0, s[46:47] offset:1024
	global_load_dwordx4 v[40:43], v0, s[42:43] offset:1024
	global_load_dwordx4 v[12:15], v0, s[46:47] offset:1088
	global_load_dwordx4 v[44:47], v0, s[42:43] offset:1088
	global_load_dwordx4 v[16:19], v0, s[46:47] offset:1152
	global_load_dwordx4 v[48:51], v0, s[42:43] offset:1152
	global_load_dwordx4 v[20:23], v0, s[46:47] offset:1216
	global_load_dwordx4 v[52:55], v0, s[42:43] offset:1216
	global_load_dwordx4 v[24:27], v0, s[46:47] offset:1280
	global_load_dwordx4 v[56:59], v0, s[42:43] offset:1280
	global_load_dwordx4 v[28:31], v0, s[46:47] offset:1344
	global_load_dwordx4 v[60:63], v0, s[42:43] offset:1344
	global_load_dwordx4 v[32:35], v0, s[46:47] offset:1408
	global_load_dwordx4 v[64:67], v0, s[42:43] offset:1408
	global_load_dwordx4 v[36:39], v0, s[46:47] offset:1472
	global_load_dwordx4 v[68:71], v0, s[42:43] offset:1472
	s_waitcnt vmcnt(30)
	v_mfma_f32_16x16x32_bf16 v[4:7], v[104:107], v[72:75], v[4:7]
	s_waitcnt vmcnt(28)
	v_mfma_f32_16x16x32_bf16 v[4:7], v[108:111], v[76:79], v[4:7]
	s_waitcnt vmcnt(26)
	v_mfma_f32_16x16x32_bf16 v[4:7], v[112:115], v[80:83], v[4:7]
	s_waitcnt vmcnt(24)
	v_mfma_f32_16x16x32_bf16 v[4:7], v[116:119], v[84:87], v[4:7]
	s_waitcnt vmcnt(22)
	v_mfma_f32_16x16x32_bf16 v[4:7], v[120:123], v[88:91], v[4:7]
	s_waitcnt vmcnt(20)
	v_mfma_f32_16x16x32_bf16 v[4:7], v[124:127], v[92:95], v[4:7]
	s_waitcnt vmcnt(18)
	v_mfma_f32_16x16x32_bf16 v[4:7], v[128:131], v[96:99], v[4:7]
	s_waitcnt vmcnt(16)
	v_mfma_f32_16x16x32_bf16 v[4:7], v[132:135], v[100:103], v[4:7]
	global_load_dwordx4 v[72:75], v0, s[46:47] offset:1536
	global_load_dwordx4 v[104:107], v0, s[42:43] offset:1536
	global_load_dwordx4 v[76:79], v0, s[46:47] offset:1600
	global_load_dwordx4 v[108:111], v0, s[42:43] offset:1600
	global_load_dwordx4 v[80:83], v0, s[46:47] offset:1664
	global_load_dwordx4 v[112:115], v0, s[42:43] offset:1664
	global_load_dwordx4 v[84:87], v0, s[46:47] offset:1728
	global_load_dwordx4 v[116:119], v0, s[42:43] offset:1728
	global_load_dwordx4 v[88:91], v0, s[46:47] offset:1792
	global_load_dwordx4 v[120:123], v0, s[42:43] offset:1792
	global_load_dwordx4 v[92:95], v0, s[46:47] offset:1856
	global_load_dwordx4 v[124:127], v0, s[42:43] offset:1856
	global_load_dwordx4 v[96:99], v0, s[46:47] offset:1920
	global_load_dwordx4 v[128:131], v0, s[42:43] offset:1920
	global_load_dwordx4 v[100:103], v0, s[46:47] offset:1984
	global_load_dwordx4 v[132:135], v0, s[42:43] offset:1984
	s_waitcnt vmcnt(30)
;     __device__ __forceinline__ void operator()(const f32x4 (&acc)[2][2][4][2], const pg8::Unit& u, int wr, int wc, int fr, int fq) const {
;     ...
;         if (pn == 44) {
;             if (wc == 0 && fq < 2) {
; #pragma unroll
;                 for (int ai = 0; ai < 2; ++ai)
; #pragma unroll
;                     for (int m = 0; m < 4; ++m) { float* gp = gates + (size_t)(row0 + ai * 128 + m * 16) * 16 + 8 * fq;
;                         *(f32x4*)gp = acc[ai][0][m][0]; *(f32x4*)(gp + 4) = acc[ai][0][m][1]; }
;             }
;             return;
	v_mfma_f32_16x16x32_bf16 v[4:7], v[40:43], v[8:11], v[4:7]
	s_waitcnt vmcnt(28)
	v_mfma_f32_16x16x32_bf16 v[4:7], v[44:47], v[12:15], v[4:7]
	s_waitcnt vmcnt(26)
	v_mfma_f32_16x16x32_bf16 v[4:7], v[48:51], v[16:19], v[4:7]
	s_waitcnt vmcnt(24)
	v_mfma_f32_16x16x32_bf16 v[4:7], v[52:55], v[20:23], v[4:7]
	s_waitcnt vmcnt(22)
	v_mfma_f32_16x16x32_bf16 v[4:7], v[56:59], v[24:27], v[4:7]
	s_waitcnt vmcnt(20)
	v_mfma_f32_16x16x32_bf16 v[4:7], v[60:63], v[28:31], v[4:7]
	s_waitcnt vmcnt(18)
	v_mfma_f32_16x16x32_bf16 v[4:7], v[64:67], v[32:35], v[4:7]
	s_waitcnt vmcnt(16)
	v_mfma_f32_16x16x32_bf16 v[4:7], v[68:71], v[36:39], v[4:7]
	global_load_dwordx4 v[8:11], v0, s[46:47] offset:2048
	global_load_dwordx4 v[40:43], v0, s[42:43] offset:2048
	global_load_dwordx4 v[12:15], v0, s[46:47] offset:2112
	global_load_dwordx4 v[44:47], v0, s[42:43] offset:2112
	global_load_dwordx4 v[16:19], v0, s[46:47] offset:2176
	global_load_dwordx4 v[48:51], v0, s[42:43] offset:2176
	global_load_dwordx4 v[20:23], v0, s[46:47] offset:2240
	global_load_dwordx4 v[52:55], v0, s[42:43] offset:2240
	global_load_dwordx4 v[24:27], v0, s[46:47] offset:2304
	global_load_dwordx4 v[56:59], v0, s[42:43] offset:2304
	global_load_dwordx4 v[28:31], v0, s[46:47] offset:2368
	global_load_dwordx4 v[60:63], v0, s[42:43] offset:2368
	global_load_dwordx4 v[32:35], v0, s[46:47] offset:2432
	global_load_dwordx4 v[64:67], v0, s[42:43] offset:2432
	global_load_dwordx4 v[36:39], v0, s[46:47] offset:2496
	global_load_dwordx4 v[68:71], v0, s[42:43] offset:2496
	s_waitcnt vmcnt(30)
	v_mfma_f32_16x16x32_bf16 v[4:7], v[104:107], v[72:75], v[4:7]
	s_waitcnt vmcnt(28)
	v_mfma_f32_16x16x32_bf16 v[4:7], v[108:111], v[76:79], v[4:7]
	s_waitcnt vmcnt(26)
	v_mfma_f32_16x16x32_bf16 v[4:7], v[112:115], v[80:83], v[4:7]
	s_waitcnt vmcnt(24)
	v_mfma_f32_16x16x32_bf16 v[4:7], v[116:119], v[84:87], v[4:7]
	s_waitcnt vmcnt(22)
	v_mfma_f32_16x16x32_bf16 v[4:7], v[120:123], v[88:91], v[4:7]
	s_waitcnt vmcnt(20)
	v_mfma_f32_16x16x32_bf16 v[4:7], v[124:127], v[92:95], v[4:7]
	s_waitcnt vmcnt(18)
	v_mfma_f32_16x16x32_bf16 v[4:7], v[128:131], v[96:99], v[4:7]
	s_waitcnt vmcnt(16)
	v_mfma_f32_16x16x32_bf16 v[4:7], v[132:135], v[100:103], v[4:7]
	global_load_dwordx4 v[72:75], v0, s[46:47] offset:2560
	global_load_dwordx4 v[104:107], v0, s[42:43] offset:2560
	global_load_dwordx4 v[76:79], v0, s[46:47] offset:2624
	global_load_dwordx4 v[108:111], v0, s[42:43] offset:2624
	global_load_dwordx4 v[80:83], v0, s[46:47] offset:2688
	global_load_dwordx4 v[112:115], v0, s[42:43] offset:2688
	global_load_dwordx4 v[84:87], v0, s[46:47] offset:2752
	global_load_dwordx4 v[116:119], v0, s[42:43] offset:2752
	global_load_dwordx4 v[88:91], v0, s[46:47] offset:2816
	global_load_dwordx4 v[120:123], v0, s[42:43] offset:2816
	global_load_dwordx4 v[92:95], v0, s[46:47] offset:2880
	global_load_dwordx4 v[124:127], v0, s[42:43] offset:2880
	global_load_dwordx4 v[96:99], v0, s[46:47] offset:2944
	global_load_dwordx4 v[128:131], v0, s[42:43] offset:2944
	global_load_dwordx4 v[100:103], v0, s[46:47] offset:3008
	global_load_dwordx4 v[132:135], v0, s[42:43] offset:3008
	s_waitcnt vmcnt(30)
	v_mfma_f32_16x16x32_bf16 v[4:7], v[40:43], v[8:11], v[4:7]
	s_waitcnt vmcnt(28)
	v_mfma_f32_16x16x32_bf16 v[4:7], v[44:47], v[12:15], v[4:7]
	s_waitcnt vmcnt(26)
	v_mfma_f32_16x16x32_bf16 v[4:7], v[48:51], v[16:19], v[4:7]
	s_waitcnt vmcnt(24)
	v_mfma_f32_16x16x32_bf16 v[4:7], v[52:55], v[20:23], v[4:7]
	s_waitcnt vmcnt(22)
	v_mfma_f32_16x16x32_bf16 v[4:7], v[56:59], v[24:27], v[4:7]
	s_waitcnt vmcnt(20)
	v_mfma_f32_16x16x32_bf16 v[4:7], v[60:63], v[28:31], v[4:7]
	s_waitcnt vmcnt(18)
	v_mfma_f32_16x16x32_bf16 v[4:7], v[64:67], v[32:35], v[4:7]
	s_waitcnt vmcnt(16)
	v_mfma_f32_16x16x32_bf16 v[4:7], v[68:71], v[36:39], v[4:7]
	global_load_dwordx4 v[8:11], v0, s[46:47] offset:3072
	global_load_dwordx4 v[40:43], v0, s[42:43] offset:3072
	global_load_dwordx4 v[12:15], v0, s[46:47] offset:3136
	global_load_dwordx4 v[44:47], v0, s[42:43] offset:3136
	global_load_dwordx4 v[16:19], v0, s[46:47] offset:3200
	global_load_dwordx4 v[48:51], v0, s[42:43] offset:3200
	global_load_dwordx4 v[20:23], v0, s[46:47] offset:3264
	global_load_dwordx4 v[52:55], v0, s[42:43] offset:3264
	global_load_dwordx4 v[24:27], v0, s[46:47] offset:3328
	global_load_dwordx4 v[56:59], v0, s[42:43] offset:3328
	global_load_dwordx4 v[28:31], v0, s[46:47] offset:3392
	global_load_dwordx4 v[60:63], v0, s[42:43] offset:3392
	global_load_dwordx4 v[32:35], v0, s[46:47] offset:3456
	global_load_dwordx4 v[64:67], v0, s[42:43] offset:3456
	global_load_dwordx4 v[36:39], v0, s[46:47] offset:3520
	global_load_dwordx4 v[68:71], v0, s[42:43] offset:3520
	s_waitcnt vmcnt(30)
;     __device__ __forceinline__ void operator()(const f32x4 (&acc)[2][2][4][2], const pg8::Unit& u, int wr, int wc, int fr, int fq) const {
;     ...
;         if (pn == 44) {
;             if (wc == 0 && fq < 2) {
; #pragma unroll
;                 for (int ai = 0; ai < 2; ++ai)
; #pragma unroll
;                     for (int m = 0; m < 4; ++m) { float* gp = gates + (size_t)(row0 + ai * 128 + m * 16) * 16 + 8 * fq;
;                         *(f32x4*)gp = acc[ai][0][m][0]; *(f32x4*)(gp + 4) = acc[ai][0][m][1]; }
;             }
;             return;
; __device__ __forceinline__ void xcd_barrier(const XcdBarrier& b) {
;     asm volatile("s_waitcnt vmcnt(0)" ::: "memory");
;     __syncthreads();
;     if (threadIdx.x == 0) {
;         unsigned* bar = b.bar;
;         __builtin_amdgcn_s_waitcnt(0);
;         unsigned nloc = b.st[0], nx = b.st[1];
;         if (nloc == 0u) { xcd_barrier_complete(bar, b.x, nloc, nx); b.st[0] = nloc; b.st[1] = nx; }
	v_mfma_f32_16x16x32_bf16 v[4:7], v[104:107], v[72:75], v[4:7]
	s_waitcnt vmcnt(28)
	v_mfma_f32_16x16x32_bf16 v[4:7], v[108:111], v[76:79], v[4:7]
	s_waitcnt vmcnt(26)
	v_mfma_f32_16x16x32_bf16 v[4:7], v[112:115], v[80:83], v[4:7]
	s_waitcnt vmcnt(24)
	v_mfma_f32_16x16x32_bf16 v[4:7], v[116:119], v[84:87], v[4:7]
	s_waitcnt vmcnt(22)
	v_mfma_f32_16x16x32_bf16 v[4:7], v[120:123], v[88:91], v[4:7]
	s_waitcnt vmcnt(20)
	v_mfma_f32_16x16x32_bf16 v[4:7], v[124:127], v[92:95], v[4:7]
	s_waitcnt vmcnt(18)
	v_mfma_f32_16x16x32_bf16 v[4:7], v[128:131], v[96:99], v[4:7]
	s_waitcnt vmcnt(16)
	v_mfma_f32_16x16x32_bf16 v[4:7], v[132:135], v[100:103], v[4:7]
	global_load_dwordx4 v[72:75], v0, s[46:47] offset:3584
	global_load_dwordx4 v[104:107], v0, s[42:43] offset:3584
	global_load_dwordx4 v[76:79], v0, s[46:47] offset:3648
	global_load_dwordx4 v[108:111], v0, s[42:43] offset:3648
	global_load_dwordx4 v[80:83], v0, s[46:47] offset:3712
	global_load_dwordx4 v[112:115], v0, s[42:43] offset:3712
	global_load_dwordx4 v[84:87], v0, s[46:47] offset:3776
	global_load_dwordx4 v[116:119], v0, s[42:43] offset:3776
	global_load_dwordx4 v[88:91], v0, s[46:47] offset:3840
	global_load_dwordx4 v[120:123], v0, s[42:43] offset:3840
	global_load_dwordx4 v[92:95], v0, s[46:47] offset:3904
	global_load_dwordx4 v[124:127], v0, s[42:43] offset:3904
	global_load_dwordx4 v[96:99], v0, s[46:47] offset:3968
	global_load_dwordx4 v[128:131], v0, s[42:43] offset:3968
	global_load_dwordx4 v[100:103], v0, s[46:47] offset:4032
	global_load_dwordx4 v[132:135], v0, s[42:43] offset:4032
	s_waitcnt vmcnt(30)
	v_mfma_f32_16x16x32_bf16 v[4:7], v[40:43], v[8:11], v[4:7]
	s_waitcnt vmcnt(28)
	v_mfma_f32_16x16x32_bf16 v[4:7], v[44:47], v[12:15], v[4:7]
	s_waitcnt vmcnt(26)
	v_mfma_f32_16x16x32_bf16 v[4:7], v[48:51], v[16:19], v[4:7]
	s_waitcnt vmcnt(24)
	v_mfma_f32_16x16x32_bf16 v[4:7], v[52:55], v[20:23], v[4:7]
	s_waitcnt vmcnt(22)
	v_mfma_f32_16x16x32_bf16 v[4:7], v[56:59], v[24:27], v[4:7]
	s_waitcnt vmcnt(20)
	v_mfma_f32_16x16x32_bf16 v[4:7], v[60:63], v[28:31], v[4:7]
	s_waitcnt vmcnt(18)
	v_mfma_f32_16x16x32_bf16 v[4:7], v[64:67], v[32:35], v[4:7]
	s_waitcnt vmcnt(16)
	v_mfma_f32_16x16x32_bf16 v[4:7], v[68:71], v[36:39], v[4:7]
	s_waitcnt vmcnt(14)
	v_mfma_f32_16x16x32_bf16 v[4:7], v[104:107], v[72:75], v[4:7]
	s_waitcnt vmcnt(12)
	v_mfma_f32_16x16x32_bf16 v[4:7], v[108:111], v[76:79], v[4:7]
	s_waitcnt vmcnt(10)
	v_mfma_f32_16x16x32_bf16 v[4:7], v[112:115], v[80:83], v[4:7]
	s_waitcnt vmcnt(8)
	v_mfma_f32_16x16x32_bf16 v[4:7], v[116:119], v[84:87], v[4:7]
	s_waitcnt vmcnt(6)
	v_mfma_f32_16x16x32_bf16 v[4:7], v[120:123], v[88:91], v[4:7]
	s_waitcnt vmcnt(4)
	v_mfma_f32_16x16x32_bf16 v[4:7], v[124:127], v[92:95], v[4:7]
	s_waitcnt vmcnt(2)
	v_mfma_f32_16x16x32_bf16 v[4:7], v[128:131], v[96:99], v[4:7]
	s_waitcnt vmcnt(0)
	v_mfma_f32_16x16x32_bf16 v[4:7], v[132:135], v[100:103], v[4:7]
	s_nop 7
	s_nop 3
	global_store_dwordx4 v2, v[4:7], s[48:49]
	s_add_i32 s38, s38, s40
	s_branch .Lgate_loop
.Lgate_done:
.LBB0_158:
	v_readlane_b32 s4, v246, 12
	v_readlane_b32 s5, v246, 13
	s_cmp_gt_i32 s5, 2
	s_cselect_b64 s[2:3], -1, 0
	s_and_b64 s[0:1], s[0:1], s[2:3]
	s_andn2_b64 vcc, exec, s[0:1]
	v_readlane_b32 s6, v246, 14
	v_readlane_b32 s7, v246, 15
	s_cbranch_vccnz .LBB0_212
	s_waitcnt vmcnt(0)
	s_waitcnt vmcnt(0)
	s_barrier
	s_mov_b64 s[0:1], exec
	v_readlane_b32 s4, v246, 23
	v_readlane_b32 s5, v246, 24
	s_and_b64 s[4:5], s[0:1], s[4:5]
	s_mov_b64 exec, s[4:5]
	s_cbranch_execz .LBB0_211
	s_add_i32 s4, 0, 0x23fe0
	v_mov_b32_e32 v0, s4
	s_waitcnt vmcnt(0) expcnt(0) lgkmcnt(0)
	ds_read_b32 v2, v0
	s_add_i32 s4, 0, 0x23fe4
	v_mov_b32_e32 v0, s4
	ds_read_b32 v0, v0
	s_waitcnt lgkmcnt(1)
	v_cmp_ne_u32_e32 vcc, 0, v2
	s_cbranch_vccnz .LBB0_175
	v_readlane_b32 s4, v246, 16
	v_readlane_b32 s5, v246, 17
	s_load_dwordx2 s[8:9], s[4:5], 0x4
	v_readlane_b32 s10, v246, 18
	v_readlane_b32 s11, v246, 19
	s_add_u32 s4, s10, 0x1000
	s_addc_u32 s5, s11, 0
	s_add_u32 s6, s10, 0x1100
	s_addc_u32 s7, s11, 0
	s_waitcnt lgkmcnt(0)
	s_mul_i32 s33, s8, s34
	s_add_u32 s8, s10, 0x1200
	s_mul_i32 s33, s33, s9
	s_addc_u32 s9, s11, 0
	s_add_u32 s10, s10, 0x1300
	s_addc_u32 s11, s11, 0
	s_mov_b32 s35, 1
	v_mov_b32_e32 v16, 0
	s_branch .LBB0_163

; __device__ __forceinline__ unsigned pk2(float lo, float hi) { unsigned r; asm("v_cvt_pk_bf16_f32 %0, %1, %2" : "=v"(r) : "v"(lo), "v"(hi)); return r; }
; __device__ __forceinline__ f32x4 mfma16(bf16x8 a, bf16x8 b, f32x4 c) { return __builtin_amdgcn_mfma_f32_16x16x32_bf16(a, b, c, 0, 0, 0); }
; #define SCAN_SB() __builtin_amdgcn_sched_barrier(0)
; __device__ __forceinline__ void scan_item(const Params& p, int item, unsigned char* lds) {
;     ...
;         bf16_t* hp = hU + (size_t)(sb * 1024 + hl);
;         float rden = 0.f;
;         {
;             bf16x8 cf[8], vf[4];
; #pragma unroll
;             for (int ks = 0; ks < 8; ++ks) cf[ks] = *(const bf16x8*)(Cs + (64 + fr) * 264 + ks * 32 + fq * 8);
; #pragma unroll
;             for (int ei = 0; ei < 5; ++ei) { const int et = (ei == 0) ? 4 : ei - 1;
;                 if (et < 4) {
; #pragma unroll
;                     for (int k2 = 0; k2 < 4; ++k2) vf[k2] = *(const bf16x8*)(Vc + (16 * et + fr) * 256 + (((k2 * 4 + fq) ^ fr) << 4));
;                 }
;                 SCAN_SB();
;                 f32x4 a = (f32x4){0.f, 0.f, 0.f, 0.f};
; #pragma unroll
;                 for (int ks = 0; ks < 8; ++ks) a = mfma16(cf[ks], qf[ks], a);
;                 SCAN_SB();
;                 if (ei < 4) {
; #pragma unroll
;                     for (int ks = 0; ks < 8; ++ks) cf[ks] = *(const bf16x8*)(Cs + (16 * ei + fr) * 264 + ks * 32 + fq * 8);
;                 }
;                 a = a * winter;
; #pragma unroll
;                 for (int k2 = 0; k2 < 4; ++k2) a = mfma16(et < 4 ? vf[k2] : onesf, pf[k2], a);
;                 if (et == 4) { const float den = __shfl(a[0], fr); rden = 1.0f / fmaxf(fabsf(den), eclamp); }
;                 else { const f32x4 v = a * rden; u32x2 wv; wv.x = pk2(v[0], v[1]); wv.y = pk2(v[2], v[3]); *(u32x2*)(hp + 16 * et) = wv; } }
.LBB0_312:
	ds_read_b128 v[146:149], v164 offset:34240
	ds_read_b128 v[192:195], v164 offset:34176
	ds_read_b128 v[196:199], v164 offset:34112
	ds_read_b128 v[200:203], v164 offset:34048
	ds_read_b128 v[204:207], v164 offset:33984
	ds_read_b128 v[208:211], v164 offset:33920
	ds_read_b128 v[212:215], v164 offset:33856
	ds_read_b128 v[216:219], v164 offset:33792
	s_add_i32 s25, s41, 0xffffff80
	s_add_i32 vcc_lo, s40, 0x80
	s_and_b64 s[36:37], s[44:45], exec
	v_sub_f32_e32 v134, v138, v140
	v_add_f32_e32 v140, v141, v140
	s_cselect_b32 s25, s25, vcc_lo
	v_mul_f32_e32 v134, 0x3fb8aa3b, v134
	v_mul_f32_e32 v140, 0xbfb8aa3b, v140
	s_lshl_b32 s25, s25, 10
	v_exp_f32_e32 v134, v134
	v_exp_f32_e32 v140, v140
	v_add_lshl_u32 v141, v154, s25, 1
	v_add_u32_e32 v142, s24, v165
	s_waitcnt lgkmcnt(0)
	v_mfma_f32_16x16x32_bf16 v[216:219], v[216:219], v[42:45], 0
	v_mfma_f32_16x16x32_bf16 v[212:215], v[212:215], v[50:53], v[216:219]
	v_mfma_f32_16x16x32_bf16 v[208:211], v[208:211], v[54:57], v[212:215]
	v_mfma_f32_16x16x32_bf16 v[204:207], v[204:207], v[58:61], v[208:211]
	v_mfma_f32_16x16x32_bf16 v[200:203], v[200:203], v[62:65], v[204:207]
	v_mfma_f32_16x16x32_bf16 v[196:199], v[196:199], v[66:69], v[200:203]
	v_mfma_f32_16x16x32_bf16 v[192:195], v[192:195], v[70:73], v[196:199]
	v_mfma_f32_16x16x32_bf16 v[146:149], v[146:149], v[74:77], v[192:195]
	s_nop 7
	v_pk_mul_f32 v[148:149], v[134:135], v[148:149] op_sel_hi:[0,1]
	v_pk_mul_f32 v[146:147], v[134:135], v[146:147] op_sel_hi:[0,1]
	ds_read_b128 v[196:199], v185
	ds_read_b128 v[200:203], v185 offset:64
	ds_read_b128 v[204:207], v185 offset:128
	ds_read_b128 v[208:211], v185 offset:192
	ds_read_b128 v[212:215], v185 offset:256
	ds_read_b128 v[216:219], v185 offset:320
	ds_read_b128 v[220:223], v185 offset:384
	ds_read_b128 v[224:227], v185 offset:448
	v_mfma_f32_16x16x32_bf16 v[146:149], v[0:3], v[118:121], v[146:149]
	v_add_u32_e32 v194, v142, v166
	v_add_u32_e32 v193, v142, v167
	v_add_u32_e32 v192, v142, v168
	v_mfma_f32_16x16x32_bf16 v[146:149], v[0:3], v[122:125], v[146:149]
	v_add_u32_e32 v191, v142, v169
	ds_read_b128 v[232:235], v192
	ds_read_b128 v[236:239], v191
	v_mfma_f32_16x16x32_bf16 v[146:149], v[0:3], v[126:129], v[146:149]
	ds_read_b128 v[228:231], v193
	v_mfma_f32_16x16x32_bf16 v[146:149], v[0:3], v[130:133], v[146:149]
	s_nop 7
	ds_bpermute_b32 v143, v188, v146
	s_waitcnt lgkmcnt(0)
	v_max_f32_e64 v143, |v143|, |v143|
	v_max_f32_e32 v140, v143, v140
	v_div_scale_f32 v143, s[24:25], v140, v140, 1.0
	v_rcp_f32_e32 v146, v143
	s_nop 0
	v_fma_f32 v147, -v143, v146, 1.0
	v_fmac_f32_e32 v146, v147, v146
	v_div_scale_f32 v147, vcc, 1.0, v140, 1.0
	v_mul_f32_e32 v148, v147, v146
	v_fma_f32 v149, -v143, v148, v147
	v_fmac_f32_e32 v148, v149, v146
	v_fma_f32 v143, -v143, v148, v147
	v_div_fmas_f32 v143, v143, v146, v148
	ds_read_b128 v[146:149], v194
	v_div_fixup_f32 v140, v143, v140, 1.0
	v_mfma_f32_16x16x32_bf16 v[196:199], v[196:199], v[42:45], 0
	v_mfma_f32_16x16x32_bf16 v[196:199], v[200:203], v[50:53], v[196:199]
	v_mfma_f32_16x16x32_bf16 v[196:199], v[204:207], v[54:57], v[196:199]
	v_mfma_f32_16x16x32_bf16 v[196:199], v[208:211], v[58:61], v[196:199]
	v_mfma_f32_16x16x32_bf16 v[196:199], v[212:215], v[62:65], v[196:199]
	v_mfma_f32_16x16x32_bf16 v[196:199], v[216:219], v[66:69], v[196:199]
	v_mfma_f32_16x16x32_bf16 v[196:199], v[220:223], v[70:73], v[196:199]
	v_mfma_f32_16x16x32_bf16 v[196:199], v[224:227], v[74:77], v[196:199]
	s_nop 7
	v_pk_mul_f32 v[198:199], v[134:135], v[198:199] op_sel_hi:[0,1]
	v_pk_mul_f32 v[196:197], v[134:135], v[196:197] op_sel_hi:[0,1]
	s_waitcnt lgkmcnt(0)
	s_nop 0
	v_mfma_f32_16x16x32_bf16 v[146:149], v[146:149], v[118:121], v[196:199]
	s_nop 2
	ds_read_b128 v[196:199], v185 offset:8448
	ds_read_b128 v[200:203], v185 offset:8512
	ds_read_b128 v[204:207], v185 offset:8576
	ds_read_b128 v[208:211], v185 offset:8640
	ds_read_b128 v[212:215], v185 offset:8704
	ds_read_b128 v[216:219], v185 offset:8768
	v_mfma_f32_16x16x32_bf16 v[146:149], v[228:231], v[122:125], v[146:149]
	v_mfma_f32_16x16x32_bf16 v[146:149], v[232:235], v[126:129], v[146:149]
	ds_read_b128 v[220:223], v185 offset:8832
	ds_read_b128 v[224:227], v185 offset:8896
	ds_read_b128 v[228:231], v194 offset:4096
	ds_read_b128 v[232:235], v193 offset:4096
	v_mfma_f32_16x16x32_bf16 v[146:149], v[236:239], v[130:133], v[146:149]
	ds_read_b128 v[236:239], v192 offset:4096
	ds_read_b128 v[240:243], v191 offset:4096
	s_nop 5
	v_pk_mul_f32 v[146:147], v[140:141], v[146:147] op_sel_hi:[0,1]
	v_pk_mul_f32 v[142:143], v[140:141], v[148:149] op_sel_hi:[0,1]
	v_cvt_pk_bf16_f32 v146, v146, v147
	v_cvt_pk_bf16_f32 v147, v142, v143
	global_store_dwordx2 v141, v[146:147], s[18:19]
	s_waitcnt lgkmcnt(11)
	v_mfma_f32_16x16x32_bf16 v[146:149], v[196:199], v[42:45], 0
	s_waitcnt lgkmcnt(10)
	v_mfma_f32_16x16x32_bf16 v[146:149], v[200:203], v[50:53], v[146:149]
	s_waitcnt lgkmcnt(9)
	v_mfma_f32_16x16x32_bf16 v[146:149], v[204:207], v[54:57], v[146:149]
	s_waitcnt lgkmcnt(8)
	v_mfma_f32_16x16x32_bf16 v[146:149], v[208:211], v[58:61], v[146:149]
	s_waitcnt lgkmcnt(7)
	v_mfma_f32_16x16x32_bf16 v[146:149], v[212:215], v[62:65], v[146:149]
	s_waitcnt lgkmcnt(6)
	v_mfma_f32_16x16x32_bf16 v[146:149], v[216:219], v[66:69], v[146:149]
	s_waitcnt lgkmcnt(5)
	v_mfma_f32_16x16x32_bf16 v[146:149], v[220:223], v[70:73], v[146:149]
	s_waitcnt lgkmcnt(4)
	v_mfma_f32_16x16x32_bf16 v[146:149], v[224:227], v[74:77], v[146:149]
	s_nop 7
	v_pk_mul_f32 v[148:149], v[134:135], v[148:149] op_sel_hi:[0,1]
	v_pk_mul_f32 v[146:147], v[134:135], v[146:147] op_sel_hi:[0,1]
	ds_read_b128 v[196:199], v185 offset:16896
	ds_read_b128 v[200:203], v185 offset:16960
	s_waitcnt lgkmcnt(5)
; #define LAS __attribute__((address_space(3)))
; __device__ __forceinline__ unsigned pk2(float lo, float hi) { unsigned r; asm("v_cvt_pk_bf16_f32 %0, %1, %2" : "=v"(r) : "v"(lo), "v"(hi)); return r; }
; __device__ __forceinline__ f32x4 mfma16(bf16x8 a, bf16x8 b, f32x4 c) { return __builtin_amdgcn_mfma_f32_16x16x32_bf16(a, b, c, 0, 0, 0); }
; __device__ __forceinline__ void scan_item(const Params& p, int item, unsigned char* lds) {
;     ...
;                 if (ei < 4) {
; #pragma unroll
;                     for (int ks = 0; ks < 8; ++ks) cf[ks] = *(const bf16x8*)(Cs + (16 * ei + fr) * 264 + ks * 32 + fq * 8);
;                 }
;                 a = a * winter;
; #pragma unroll
;                 for (int k2 = 0; k2 < 4; ++k2) a = mfma16(et < 4 ? vf[k2] : onesf, pf[k2], a);
;                 if (et == 4) { const float den = __shfl(a[0], fr); rden = 1.0f / fmaxf(fabsf(den), eclamp); }
;                 else { const f32x4 v = a * rden; u32x2 wv; wv.x = pk2(v[0], v[1]); wv.y = pk2(v[2], v[3]); *(u32x2*)(hp + 16 * et) = wv; } }
;         }
;         u32x2 ktr[2][4][2];
; #pragma unroll
;         for (int dd = 0; dd < 2; ++dd)
; #pragma unroll
;             for (int k2 = 0; k2 < 4; ++k2)
; #pragma unroll
;                 for (int hf = 0; hf < 2; ++hf) { const int row = 32 * k2 + 16 * hf + 4 * fq + (fr >> 2), ch = 4 * w + 2 * dd + ((fr & 3) >> 1);
;                     typedef short v4i16_t __attribute__((ext_vector_type(4)));
;                     const v4i16_t tv = __builtin_amdgcn_ds_read_tr16_b64_v4i16((LAS v4i16_t*)(LAS unsigned char*)(Ks + row * 512 + ((ch ^ (row & 15)) << 4) + 8 * (fr & 1)));
;                     ktr[dd][k2][hf] = __builtin_bit_cast(u32x2, tv); }
;         __syncthreads();
;     ...
;         if (c + 1 < 32) { const bf16_t* qrow = qU + (size_t)(sbn * 1024 + ql);
; #pragma unroll
;             for (int ks = 0; ks < 8; ++ks) qf[ks] = *(const bf16x8*)(qrow + ks * 32); }
	v_mfma_f32_16x16x32_bf16 v[146:149], v[228:231], v[118:121], v[146:149]
	ds_read_b128 v[204:207], v185 offset:17024
	ds_read_b128 v[208:211], v185 offset:17088
	ds_read_b128 v[212:215], v185 offset:17152
	ds_read_b128 v[216:219], v185 offset:17216
	s_waitcnt lgkmcnt(8)
	v_mfma_f32_16x16x32_bf16 v[146:149], v[232:235], v[122:125], v[146:149]
	ds_read_b128 v[220:223], v185 offset:17280
	ds_read_b128 v[224:227], v185 offset:17344
	ds_read_b128 v[228:231], v194 offset:8192
	ds_read_b128 v[232:235], v193 offset:8192
	s_waitcnt lgkmcnt(11)
	v_mfma_f32_16x16x32_bf16 v[146:149], v[236:239], v[126:129], v[146:149]
	s_waitcnt lgkmcnt(10)
	v_mfma_f32_16x16x32_bf16 v[146:149], v[240:243], v[130:133], v[146:149]
	ds_read_b128 v[236:239], v192 offset:8192
	ds_read_b128 v[240:243], v191 offset:8192
	s_nop 5
	v_pk_mul_f32 v[146:147], v[140:141], v[146:147] op_sel_hi:[0,1]
	v_pk_mul_f32 v[142:143], v[140:141], v[148:149] op_sel_hi:[0,1]
	v_cvt_pk_bf16_f32 v146, v146, v147
	v_cvt_pk_bf16_f32 v147, v142, v143
	global_store_dwordx2 v141, v[146:147], s[18:19] offset:32
	s_waitcnt lgkmcnt(11)
	v_mfma_f32_16x16x32_bf16 v[146:149], v[196:199], v[42:45], 0
	s_waitcnt lgkmcnt(10)
	v_mfma_f32_16x16x32_bf16 v[146:149], v[200:203], v[50:53], v[146:149]
	s_waitcnt lgkmcnt(9)
	v_mfma_f32_16x16x32_bf16 v[146:149], v[204:207], v[54:57], v[146:149]
	s_waitcnt lgkmcnt(8)
	v_mfma_f32_16x16x32_bf16 v[146:149], v[208:211], v[58:61], v[146:149]
	s_waitcnt lgkmcnt(7)
	v_mfma_f32_16x16x32_bf16 v[146:149], v[212:215], v[62:65], v[146:149]
	s_waitcnt lgkmcnt(6)
	v_mfma_f32_16x16x32_bf16 v[146:149], v[216:219], v[66:69], v[146:149]
	s_waitcnt lgkmcnt(5)
	v_mfma_f32_16x16x32_bf16 v[146:149], v[220:223], v[70:73], v[146:149]
	s_waitcnt lgkmcnt(4)
	v_mfma_f32_16x16x32_bf16 v[146:149], v[224:227], v[74:77], v[146:149]
	s_nop 7
	v_pk_mul_f32 v[148:149], v[134:135], v[148:149] op_sel_hi:[0,1]
	v_pk_mul_f32 v[146:147], v[134:135], v[146:147] op_sel_hi:[0,1]
	ds_read_b128 v[196:199], v185 offset:25344
	ds_read_b128 v[200:203], v185 offset:25408
	s_waitcnt lgkmcnt(5)
	v_mfma_f32_16x16x32_bf16 v[146:149], v[228:231], v[118:121], v[146:149]
	ds_read_b128 v[204:207], v185 offset:25472
	ds_read_b128 v[208:211], v185 offset:25536
	ds_read_b128 v[212:215], v185 offset:25600
	ds_read_b128 v[216:219], v185 offset:25664
	s_waitcnt lgkmcnt(8)
	v_mfma_f32_16x16x32_bf16 v[146:149], v[232:235], v[122:125], v[146:149]
	ds_read_b128 v[220:223], v185 offset:25728
	ds_read_b128 v[224:227], v185 offset:25792
	ds_read_b128 v[228:231], v194 offset:12288
	ds_read_b128 v[232:235], v193 offset:12288
	s_waitcnt lgkmcnt(11)
	v_mfma_f32_16x16x32_bf16 v[146:149], v[236:239], v[126:129], v[146:149]
	s_waitcnt lgkmcnt(10)
	v_mfma_f32_16x16x32_bf16 v[146:149], v[240:243], v[130:133], v[146:149]
	ds_read_b128 v[236:239], v192 offset:12288
	ds_read_b128 v[240:243], v191 offset:12288
	s_nop 5
	v_pk_mul_f32 v[146:147], v[140:141], v[146:147] op_sel_hi:[0,1]
	v_pk_mul_f32 v[142:143], v[140:141], v[148:149] op_sel_hi:[0,1]
	v_cvt_pk_bf16_f32 v146, v146, v147
	v_cvt_pk_bf16_f32 v147, v142, v143
	global_store_dwordx2 v141, v[146:147], s[18:19] offset:64
	s_waitcnt lgkmcnt(11)
	v_mfma_f32_16x16x32_bf16 v[146:149], v[196:199], v[42:45], 0
	s_waitcnt lgkmcnt(10)
	v_mfma_f32_16x16x32_bf16 v[146:149], v[200:203], v[50:53], v[146:149]
	s_waitcnt lgkmcnt(9)
	v_mfma_f32_16x16x32_bf16 v[146:149], v[204:207], v[54:57], v[146:149]
	s_waitcnt lgkmcnt(8)
	v_mfma_f32_16x16x32_bf16 v[146:149], v[208:211], v[58:61], v[146:149]
	s_waitcnt lgkmcnt(7)
	v_mfma_f32_16x16x32_bf16 v[146:149], v[212:215], v[62:65], v[146:149]
	s_waitcnt lgkmcnt(6)
	v_mfma_f32_16x16x32_bf16 v[146:149], v[216:219], v[66:69], v[146:149]
	s_waitcnt lgkmcnt(5)
	v_mfma_f32_16x16x32_bf16 v[146:149], v[220:223], v[70:73], v[146:149]
	s_waitcnt lgkmcnt(4)
	v_mfma_f32_16x16x32_bf16 v[146:149], v[224:227], v[74:77], v[146:149]
	s_nop 7
	v_pk_mul_f32 v[148:149], v[134:135], v[148:149] op_sel_hi:[0,1]
	v_pk_mul_f32 v[146:147], v[134:135], v[146:147] op_sel_hi:[0,1]
	v_add_u32_e32 v134, v176, v175
	ds_read_b64_tr_b16 v[208:209], v186 offset:47104
	ds_read_b64_tr_b16 v[210:211], v186 offset:55296
	s_waitcnt lgkmcnt(5)
	v_mfma_f32_16x16x32_bf16 v[118:121], v[228:231], v[118:121], v[146:149]
	s_nop 2
	ds_read_b64_tr_b16 v[146:147], v186 offset:63488
	ds_read_b64_tr_b16 v[142:143], v134
	v_add_u32_e32 v134, v179, v174
	s_andn2_b64 vcc, exec, s[22:23]
	s_waitcnt lgkmcnt(6)
	v_mfma_f32_16x16x32_bf16 v[118:121], v[232:235], v[122:125], v[118:121]
	v_add_u32_e32 v122, v178, v177
	v_add_u32_e32 v124, v178, v174
	v_add_u32_e32 v123, v176, v177
	s_waitcnt lgkmcnt(5)
	v_mfma_f32_16x16x32_bf16 v[118:121], v[236:239], v[126:129], v[118:121]
	v_add_u32_e32 v126, v176, v174
	s_waitcnt lgkmcnt(4)
	v_mfma_f32_16x16x32_bf16 v[118:121], v[240:243], v[130:133], v[118:121]
	s_nop 7
	v_pk_mul_f32 v[118:119], v[140:141], v[118:119] op_sel_hi:[0,1]
	v_cvt_pk_bf16_f32 v118, v118, v119
	v_pk_mul_f32 v[120:121], v[140:141], v[120:121] op_sel_hi:[0,1]
	v_cvt_pk_bf16_f32 v119, v120, v121
	global_store_dwordx2 v141, v[118:119], s[18:19] offset:96
	v_add_u32_e32 v118, v179, v175
	ds_read_b64_tr_b16 v[132:133], v122
	ds_read_b64_tr_b16 v[128:129], v123
	ds_read_b64_tr_b16 v[124:125], v124
	ds_read_b64_tr_b16 v[120:121], v126
	ds_read_b64_tr_b16 v[212:213], v187 offset:47104
	ds_read_b64_tr_b16 v[214:215], v187 offset:55296
	ds_read_b64_tr_b16 v[148:149], v187 offset:63488
	ds_read_b64_tr_b16 v[140:141], v118
	v_add_u32_e32 v118, v180, v177
	v_add_u32_e32 v119, v179, v177
	v_add_u32_e32 v122, v180, v174
	ds_read_b64_tr_b16 v[130:131], v118
	ds_read_b64_tr_b16 v[126:127], v119
	ds_read_b64_tr_b16 v[122:123], v122
	ds_read_b64_tr_b16 v[118:119], v134
	s_waitcnt lgkmcnt(0)
	s_barrier
	s_cbranch_vccnz .Lscan_noq
	v_lshl_add_u32 v134, s43, 10, v158
	v_lshl_add_u64 v[74:75], v[134:135], 1, s[14:15]
	global_load_dwordx4 v[42:45], v[74:75], off
	global_load_dwordx4 v[50:53], v[74:75], off offset:64
	global_load_dwordx4 v[54:57], v[74:75], off offset:128
	global_load_dwordx4 v[58:61], v[74:75], off offset:192
	global_load_dwordx4 v[62:65], v[74:75], off offset:256
	global_load_dwordx4 v[66:69], v[74:75], off offset:320
	global_load_dwordx4 v[70:73], v[74:75], off offset:384
	s_nop 0
	global_load_dwordx4 v[74:77], v[74:75], off offset:448
; __device__ __forceinline__ unsigned pk2(float lo, float hi) { unsigned r; asm("v_cvt_pk_bf16_f32 %0, %1, %2" : "=v"(r) : "v"(lo), "v"(hi)); return r; }
; __device__ __forceinline__ f32x4 mfma16(bf16x8 a, bf16x8 b, f32x4 c) { return __builtin_amdgcn_mfma_f32_16x16x32_bf16(a, b, c, 0, 0, 0); }
; __device__ __forceinline__ void scan_item(const Params& p, int item, unsigned char* lds) {
;     ...
;         const float decay = __expf(bl + m_st - m_nw);
; #pragma unroll
;         for (int dd = 0; dd < 2; ++dd)
; #pragma unroll
;             for (int et = 0; et < 5; ++et) stC[dd][et] = stC[dd][et] * decay;
;         {
;             bf16x8 vf[4]; f32x4 avv[2];
; #pragma unroll
;             for (int k2 = 0; k2 < 4; ++k2) {
; #pragma unroll
;                 for (int et = 0; et < 4; ++et) vf[et] = *(const bf16x8*)(Vc + (16 * et + fr) * 256 + (((k2 * 4 + fq) ^ fr) << 4));
;                 avv[0] = *(const f32x4*)(SCc + 32 * k2 + 4 * fq); avv[1] = *(const f32x4*)(SCc + 32 * k2 + 16 + 4 * fq);
;                 float wsv[8];
; #pragma unroll
;                 for (int hf = 0; hf < 2; ++hf)
; #pragma unroll
;                     for (int j = 0; j < 4; ++j) wsv[4 * hf + j] = __expf(bl + avv[hf][j] - m_nw);
;                 bf16x8 kt[2];
; #pragma unroll
;                 for (int dd = 0; dd < 2; ++dd) { const u32x2 lo = ktr[dd][k2][0], hi = ktr[dd][k2][1];
;                     u32x4 wv; wv.x = pk2(bflo(lo.x) * wsv[0], bfhi(lo.x) * wsv[1]); wv.y = pk2(bflo(lo.y) * wsv[2], bfhi(lo.y) * wsv[3]);
;                     wv.z = pk2(bflo(hi.x) * wsv[4], bfhi(hi.x) * wsv[5]); wv.w = pk2(bflo(hi.y) * wsv[6], bfhi(hi.y) * wsv[7]); kt[dd] = __builtin_bit_cast(bf16x8, wv); }
; #pragma unroll
;                 for (int et = 0; et < 5; ++et) { const bf16x8 vv = et < 4 ? vf[et] : onesf;
;                     stC[0][et] = mfma16(vv, kt[0], stC[0][et]); stC[1][et] = mfma16(vv, kt[1], stC[1][et]); }
.Lscan_noq:
	ds_read_b128 v[196:199], v190 offset:43520
	v_add_f32_e32 v134, v138, v189
	ds_read_b128 v[200:203], v194
	ds_read_b128 v[204:207], v190 offset:43584
	v_sub_f32_e32 v134, v134, v139
	v_mul_f32_e32 v134, 0x3fb8aa3b, v134
	s_waitcnt lgkmcnt(2)
	v_add_f32_e32 v138, v189, v196
	v_add_f32_e32 v196, v189, v198
	v_sub_f32_e32 v196, v196, v139
	v_mul_f32_e32 v196, 0x3fb8aa3b, v196
	v_exp_f32_e32 v216, v196
	v_add_f32_e32 v196, v189, v199
	v_sub_f32_e32 v196, v196, v139
	v_mul_f32_e32 v196, 0x3fb8aa3b, v196
	v_exp_f32_e32 v217, v196
	s_waitcnt lgkmcnt(0)
	v_add_f32_e32 v196, v189, v204
	v_sub_f32_e32 v196, v196, v139
	v_mul_f32_e32 v196, 0x3fb8aa3b, v196
	v_exp_f32_e32 v218, v196
	v_add_f32_e32 v196, v189, v205
	v_sub_f32_e32 v196, v196, v139
	v_mul_f32_e32 v196, 0x3fb8aa3b, v196
	v_add_f32_e32 v195, v189, v197
	v_exp_f32_e32 v219, v196
	v_add_f32_e32 v196, v189, v206
	v_sub_f32_e32 v138, v138, v139
	v_sub_f32_e32 v195, v195, v139
	v_sub_f32_e32 v196, v196, v139
	v_mul_f32_e32 v138, 0x3fb8aa3b, v138
	v_mul_f32_e32 v195, 0x3fb8aa3b, v195
	v_mul_f32_e32 v196, 0x3fb8aa3b, v196
	v_exp_f32_e32 v138, v138
	v_exp_f32_e32 v195, v195
	v_exp_f32_e32 v220, v196
	v_add_f32_e32 v196, v189, v207
	v_sub_f32_e32 v196, v196, v139
	v_mul_f32_e32 v196, 0x3fb8aa3b, v196
	v_exp_f32_e32 v207, v196
	v_lshlrev_b32_e32 v196, 16, v208
	v_and_b32_e32 v197, 0xffff0000, v208
	v_mul_f32_e32 v196, v138, v196
	v_mul_f32_e32 v197, v195, v197
	v_cvt_pk_bf16_f32 v196, v196, v197
	v_lshlrev_b32_e32 v197, 16, v209
	v_and_b32_e32 v198, 0xffff0000, v209
	v_mul_f32_e32 v197, v216, v197
	v_mul_f32_e32 v198, v217, v198
	v_cvt_pk_bf16_f32 v197, v197, v198
	v_lshlrev_b32_e32 v198, 16, v210
	v_and_b32_e32 v199, 0xffff0000, v210
	v_mul_f32_e32 v198, v218, v198
	v_mul_f32_e32 v199, v219, v199
	v_cvt_pk_bf16_f32 v198, v198, v199
	v_lshlrev_b32_e32 v199, 16, v211
	v_and_b32_e32 v204, 0xffff0000, v211
	v_mul_f32_e32 v199, v220, v199
	v_mul_f32_e32 v204, v207, v204
	v_cvt_pk_bf16_f32 v199, v199, v204
	v_lshlrev_b32_e32 v204, 16, v212
	v_mul_f32_e32 v138, v138, v204
	v_and_b32_e32 v204, 0xffff0000, v212
	v_mul_f32_e32 v195, v195, v204
	v_exp_f32_e32 v134, v134
	v_cvt_pk_bf16_f32 v204, v138, v195
	v_lshlrev_b32_e32 v138, 16, v213
	v_and_b32_e32 v195, 0xffff0000, v213
	v_mul_f32_e32 v138, v216, v138
	v_mul_f32_e32 v195, v217, v195
	v_cvt_pk_bf16_f32 v205, v138, v195
	v_lshlrev_b32_e32 v138, 16, v214
	v_and_b32_e32 v195, 0xffff0000, v214
	v_mul_f32_e32 v138, v218, v138
	v_mul_f32_e32 v195, v219, v195
	v_pk_mul_f32 v[116:117], v[116:117], v[134:135] op_sel_hi:[1,0]
	v_pk_mul_f32 v[114:115], v[114:115], v[134:135] op_sel_hi:[1,0]
	v_pk_mul_f32 v[112:113], v[112:113], v[134:135] op_sel_hi:[1,0]
	v_pk_mul_f32 v[110:111], v[110:111], v[134:135] op_sel_hi:[1,0]
	v_cvt_pk_bf16_f32 v206, v138, v195
	v_lshlrev_b32_e32 v138, 16, v215
	v_and_b32_e32 v195, 0xffff0000, v215
	v_mul_f32_e32 v138, v220, v138
	v_mfma_f32_16x16x32_bf16 v[114:117], v[200:203], v[196:199], v[114:117]
	v_mul_f32_e32 v195, v207, v195
	v_cvt_pk_bf16_f32 v207, v138, v195
	v_pk_mul_f32 v[108:109], v[108:109], v[134:135] op_sel_hi:[1,0]
	v_mfma_f32_16x16x32_bf16 v[110:113], v[200:203], v[204:207], v[110:113]
	ds_read_b128 v[200:203], v194 offset:4096
	v_pk_mul_f32 v[106:107], v[106:107], v[134:135] op_sel_hi:[1,0]
	v_pk_mul_f32 v[100:101], v[100:101], v[134:135] op_sel_hi:[1,0]
	v_pk_mul_f32 v[98:99], v[98:99], v[134:135] op_sel_hi:[1,0]
	s_waitcnt lgkmcnt(0)
	v_mfma_f32_16x16x32_bf16 v[106:109], v[200:203], v[196:199], v[106:109]
	v_mul_f32_e64 v104, v104, v134
	v_mul_f32_e64 v105, v105, v134
	v_pk_mul_f32 v[102:103], v[102:103], v[134:135] op_sel_hi:[1,0]
	v_pk_mul_f32 v[92:93], v[92:93], v[134:135] op_sel_hi:[1,0]
	v_mfma_f32_16x16x32_bf16 v[98:101], v[200:203], v[204:207], v[98:101]
	ds_read_b128 v[200:203], v194 offset:8192
	v_pk_mul_f32 v[90:91], v[90:91], v[134:135] op_sel_hi:[1,0]
	v_pk_mul_f32 v[96:97], v[96:97], v[134:135] op_sel_hi:[1,0]
	s_waitcnt lgkmcnt(0)
	v_mfma_f32_16x16x32_bf16 v[102:105], v[200:203], v[196:199], v[102:105]
	v_mul_f32_e64 v94, v94, v134
	v_mul_f32_e64 v95, v95, v134
	v_pk_mul_f32 v[88:89], v[88:89], v[134:135] op_sel_hi:[1,0]
	v_pk_mul_f32 v[86:87], v[86:87], v[134:135] op_sel_hi:[1,0]
	v_mfma_f32_16x16x32_bf16 v[90:93], v[200:203], v[204:207], v[90:93]
	ds_read_b128 v[200:203], v194 offset:12288
	v_pk_mul_f32 v[84:85], v[84:85], v[134:135] op_sel_hi:[1,0]
	v_pk_mul_f32 v[82:83], v[82:83], v[134:135] op_sel_hi:[1,0]
	s_waitcnt lgkmcnt(0)
	v_mfma_f32_16x16x32_bf16 v[94:97], v[200:203], v[196:199], v[94:97]
	v_mul_f32_e64 v80, v80, v134
	v_mul_f32_e64 v81, v81, v134
	v_pk_mul_f32 v[78:79], v[78:79], v[134:135] op_sel_hi:[1,0]
	v_mfma_f32_16x16x32_bf16 v[86:89], v[0:3], v[196:199], v[86:89]
	ds_read_b128 v[194:197], v190 offset:43648
	s_waitcnt lgkmcnt(0)
	v_add_f32_e32 v134, v189, v194
	v_add_f32_e32 v194, v189, v196
	v_mfma_f32_16x16x32_bf16 v[82:85], v[200:203], v[204:207], v[82:85]
	v_sub_f32_e32 v194, v194, v139
	v_mul_f32_e32 v194, 0x3fb8aa3b, v194
	v_add_f32_e32 v138, v189, v195
	v_mfma_f32_16x16x32_bf16 v[78:81], v[0:3], v[204:207], v[78:81]
	ds_read_b128 v[198:201], v193
	ds_read_b128 v[202:205], v190 offset:43712
	v_exp_f32_e32 v206, v194
	v_add_f32_e32 v194, v189, v197
	v_sub_f32_e32 v194, v194, v139
	v_mul_f32_e32 v194, 0x3fb8aa3b, v194
	v_exp_f32_e32 v207, v194
	s_waitcnt lgkmcnt(0)
; __device__ __forceinline__ unsigned pk2(float lo, float hi) { unsigned r; asm("v_cvt_pk_bf16_f32 %0, %1, %2" : "=v"(r) : "v"(lo), "v"(hi)); return r; }
; __device__ __forceinline__ f32x4 mfma16(bf16x8 a, bf16x8 b, f32x4 c) { return __builtin_amdgcn_mfma_f32_16x16x32_bf16(a, b, c, 0, 0, 0); }
; __device__ __forceinline__ void scan_item(const Params& p, int item, unsigned char* lds) {
;     ...
;             for (int k2 = 0; k2 < 4; ++k2) {
; #pragma unroll
;                 for (int et = 0; et < 4; ++et) vf[et] = *(const bf16x8*)(Vc + (16 * et + fr) * 256 + (((k2 * 4 + fq) ^ fr) << 4));
;                 avv[0] = *(const f32x4*)(SCc + 32 * k2 + 4 * fq); avv[1] = *(const f32x4*)(SCc + 32 * k2 + 16 + 4 * fq);
;                 float wsv[8];
; #pragma unroll
;                 for (int hf = 0; hf < 2; ++hf)
; #pragma unroll
;                     for (int j = 0; j < 4; ++j) wsv[4 * hf + j] = __expf(bl + avv[hf][j] - m_nw);
;                 bf16x8 kt[2];
; #pragma unroll
;                 for (int dd = 0; dd < 2; ++dd) { const u32x2 lo = ktr[dd][k2][0], hi = ktr[dd][k2][1];
;                     u32x4 wv; wv.x = pk2(bflo(lo.x) * wsv[0], bfhi(lo.x) * wsv[1]); wv.y = pk2(bflo(lo.y) * wsv[2], bfhi(lo.y) * wsv[3]);
;                     wv.z = pk2(bflo(hi.x) * wsv[4], bfhi(hi.x) * wsv[5]); wv.w = pk2(bflo(hi.y) * wsv[6], bfhi(hi.y) * wsv[7]); kt[dd] = __builtin_bit_cast(bf16x8, wv); }
; #pragma unroll
;                 for (int et = 0; et < 5; ++et) { const bf16x8 vv = et < 4 ? vf[et] : onesf;
;                     stC[0][et] = mfma16(vv, kt[0], stC[0][et]); stC[1][et] = mfma16(vv, kt[1], stC[1][et]); }
	v_add_f32_e32 v194, v189, v202
	v_sub_f32_e32 v194, v194, v139
	v_mul_f32_e32 v194, 0x3fb8aa3b, v194
	v_exp_f32_e32 v202, v194
	v_add_f32_e32 v194, v189, v203
	v_sub_f32_e32 v194, v194, v139
	v_mul_f32_e32 v194, 0x3fb8aa3b, v194
	v_exp_f32_e32 v203, v194
	v_add_f32_e32 v194, v189, v204
	v_sub_f32_e32 v134, v134, v139
	v_sub_f32_e32 v138, v138, v139
	v_sub_f32_e32 v194, v194, v139
	v_mul_f32_e32 v134, 0x3fb8aa3b, v134
	v_mul_f32_e32 v138, 0x3fb8aa3b, v138
	v_mul_f32_e32 v194, 0x3fb8aa3b, v194
	v_exp_f32_e32 v134, v134
	v_exp_f32_e32 v138, v138
	v_exp_f32_e32 v204, v194
	v_add_f32_e32 v194, v189, v205
	v_sub_f32_e32 v194, v194, v139
	v_mul_f32_e32 v194, 0x3fb8aa3b, v194
	v_exp_f32_e32 v205, v194
	v_lshlrev_b32_e32 v194, 16, v146
	v_and_b32_e32 v146, 0xffff0000, v146
	v_mul_f32_e32 v194, v134, v194
	v_mul_f32_e32 v146, v138, v146
	v_cvt_pk_bf16_f32 v194, v194, v146
	v_lshlrev_b32_e32 v146, 16, v147
	v_mul_f32_e32 v146, v206, v146
	v_and_b32_e32 v147, 0xffff0000, v147
	v_mul_f32_e32 v147, v207, v147
	v_cvt_pk_bf16_f32 v195, v146, v147
	v_lshlrev_b32_e32 v146, 16, v142
	v_and_b32_e32 v142, 0xffff0000, v142
	v_mul_f32_e32 v142, v203, v142
	v_mul_f32_e32 v146, v202, v146
	v_cvt_pk_bf16_f32 v196, v146, v142
	v_lshlrev_b32_e32 v142, 16, v143
	v_mul_f32_e32 v142, v204, v142
	v_and_b32_e32 v143, 0xffff0000, v143
	v_mul_f32_e32 v143, v205, v143
	v_cvt_pk_bf16_f32 v197, v142, v143
	v_lshlrev_b32_e32 v142, 16, v148
	v_mul_f32_e32 v134, v134, v142
	v_and_b32_e32 v142, 0xffff0000, v148
	v_mul_f32_e32 v138, v138, v142
	v_cvt_pk_bf16_f32 v146, v134, v138
	v_lshlrev_b32_e32 v134, 16, v149
	v_and_b32_e32 v138, 0xffff0000, v149
	v_mul_f32_e32 v134, v206, v134
	v_mul_f32_e32 v138, v207, v138
	v_cvt_pk_bf16_f32 v147, v134, v138
	v_lshlrev_b32_e32 v134, 16, v140
	v_and_b32_e32 v138, 0xffff0000, v140
	v_mul_f32_e32 v134, v202, v134
	v_mul_f32_e32 v138, v203, v138
	v_cvt_pk_bf16_f32 v148, v134, v138
	v_lshlrev_b32_e32 v134, 16, v141
	v_and_b32_e32 v138, 0xffff0000, v141
	ds_read_b128 v[140:143], v193 offset:4096
	v_mul_f32_e32 v134, v204, v134
	v_mul_f32_e32 v138, v205, v138
	v_cvt_pk_bf16_f32 v149, v134, v138
	s_waitcnt lgkmcnt(0)
	v_mfma_f32_16x16x32_bf16 v[106:109], v[140:143], v[194:197], v[106:109]
	v_mfma_f32_16x16x32_bf16 v[98:101], v[140:143], v[146:149], v[98:101]
	ds_read_b128 v[140:143], v193 offset:8192
	s_waitcnt lgkmcnt(0)
	v_mfma_f32_16x16x32_bf16 v[102:105], v[140:143], v[194:197], v[102:105]
	v_mfma_f32_16x16x32_bf16 v[90:93], v[140:143], v[146:149], v[90:93]
	ds_read_b128 v[140:143], v193 offset:12288
	s_waitcnt lgkmcnt(0)
	v_mfma_f32_16x16x32_bf16 v[94:97], v[140:143], v[194:197], v[94:97]
	v_mfma_f32_16x16x32_bf16 v[82:85], v[140:143], v[146:149], v[82:85]
	ds_read_b128 v[140:143], v190 offset:43776
	s_waitcnt lgkmcnt(0)
	v_add_f32_e32 v134, v189, v140
	v_add_f32_e32 v140, v189, v142
	v_mfma_f32_16x16x32_bf16 v[114:117], v[198:201], v[194:197], v[114:117]
	v_sub_f32_e32 v140, v140, v139
	v_mul_f32_e32 v140, 0x3fb8aa3b, v140
	v_exp_f32_e32 v193, v140
	v_mfma_f32_16x16x32_bf16 v[110:113], v[198:201], v[146:149], v[110:113]
	v_add_f32_e32 v140, v189, v143
	v_sub_f32_e32 v140, v140, v139
	v_mul_f32_e32 v140, 0x3fb8aa3b, v140
	v_mfma_f32_16x16x32_bf16 v[86:89], v[0:3], v[194:197], v[86:89]
	v_exp_f32_e32 v198, v140
	v_add_f32_e32 v138, v189, v141
	v_sub_f32_e32 v134, v134, v139
	v_mfma_f32_16x16x32_bf16 v[78:81], v[0:3], v[146:149], v[78:81]
	ds_read_b128 v[146:149], v192
	ds_read_b128 v[194:197], v190 offset:43840
	v_sub_f32_e32 v138, v138, v139
	v_mul_f32_e32 v134, 0x3fb8aa3b, v134
	v_mul_f32_e32 v138, 0x3fb8aa3b, v138
	v_exp_f32_e32 v134, v134
	s_waitcnt lgkmcnt(0)
	v_add_f32_e32 v140, v189, v194
	v_sub_f32_e32 v140, v140, v139
	v_mul_f32_e32 v140, 0x3fb8aa3b, v140
	v_exp_f32_e32 v194, v140
	v_add_f32_e32 v140, v189, v195
	v_sub_f32_e32 v140, v140, v139
	v_mul_f32_e32 v140, 0x3fb8aa3b, v140
	v_exp_f32_e32 v195, v140
	v_add_f32_e32 v140, v189, v196
	v_sub_f32_e32 v140, v140, v139
	v_mul_f32_e32 v140, 0x3fb8aa3b, v140
	v_exp_f32_e32 v138, v138
	v_exp_f32_e32 v196, v140
	v_add_f32_e32 v140, v189, v197
	v_sub_f32_e32 v140, v140, v139
	v_mul_f32_e32 v140, 0x3fb8aa3b, v140
	v_exp_f32_e32 v197, v140
	v_lshlrev_b32_e32 v140, 16, v132
	v_and_b32_e32 v132, 0xffff0000, v132
	v_mul_f32_e32 v140, v134, v140
	v_mul_f32_e32 v132, v138, v132
	v_cvt_pk_bf16_f32 v140, v140, v132
	v_lshlrev_b32_e32 v132, 16, v133
	v_mul_f32_e32 v132, v193, v132
	v_and_b32_e32 v133, 0xffff0000, v133
	v_mul_f32_e32 v133, v198, v133
	v_cvt_pk_bf16_f32 v141, v132, v133
	v_lshlrev_b32_e32 v132, 16, v128
	v_and_b32_e32 v128, 0xffff0000, v128
	v_mul_f32_e32 v128, v195, v128
	v_mul_f32_e32 v132, v194, v132
	v_cvt_pk_bf16_f32 v142, v132, v128
	v_lshlrev_b32_e32 v128, 16, v129
	v_and_b32_e32 v129, 0xffff0000, v129
	v_mul_f32_e32 v128, v196, v128
	v_mul_f32_e32 v129, v197, v129
	v_cvt_pk_bf16_f32 v143, v128, v129
	v_lshlrev_b32_e32 v128, 16, v130
	v_and_b32_e32 v129, 0xffff0000, v130
	v_mul_f32_e32 v128, v134, v128
	v_mul_f32_e32 v129, v138, v129
	v_cvt_pk_bf16_f32 v128, v128, v129
	v_lshlrev_b32_e32 v129, 16, v131
	v_and_b32_e32 v130, 0xffff0000, v131
	v_mul_f32_e32 v129, v193, v129
	v_mul_f32_e32 v130, v198, v130
	v_cvt_pk_bf16_f32 v129, v129, v130
	v_lshlrev_b32_e32 v130, 16, v126
	v_and_b32_e32 v126, 0xffff0000, v126
	v_mul_f32_e32 v130, v194, v130
	v_mul_f32_e32 v126, v195, v126
	v_cvt_pk_bf16_f32 v130, v130, v126
	v_lshlrev_b32_e32 v126, 16, v127
	v_and_b32_e32 v127, 0xffff0000, v127
	v_mul_f32_e32 v126, v196, v126
	v_mfma_f32_16x16x32_bf16 v[114:117], v[146:149], v[140:143], v[114:117]
	v_mul_f32_e32 v127, v197, v127
	v_cvt_pk_bf16_f32 v131, v126, v127
	s_nop 0
	v_mfma_f32_16x16x32_bf16 v[110:113], v[146:149], v[128:131], v[110:113]
	ds_read_b128 v[146:149], v192 offset:4096
	s_waitcnt lgkmcnt(0)
; __device__ __forceinline__ unsigned pk2(float lo, float hi) { unsigned r; asm("v_cvt_pk_bf16_f32 %0, %1, %2" : "=v"(r) : "v"(lo), "v"(hi)); return r; }
; __device__ __forceinline__ f32x4 mfma16(bf16x8 a, bf16x8 b, f32x4 c) { return __builtin_amdgcn_mfma_f32_16x16x32_bf16(a, b, c, 0, 0, 0); }
; __device__ __forceinline__ void scan_item(const Params& p, int item, unsigned char* lds) {
;     ...
;             for (int k2 = 0; k2 < 4; ++k2) {
; #pragma unroll
;                 for (int et = 0; et < 4; ++et) vf[et] = *(const bf16x8*)(Vc + (16 * et + fr) * 256 + (((k2 * 4 + fq) ^ fr) << 4));
;                 avv[0] = *(const f32x4*)(SCc + 32 * k2 + 4 * fq); avv[1] = *(const f32x4*)(SCc + 32 * k2 + 16 + 4 * fq);
;                 float wsv[8];
; #pragma unroll
;                 for (int hf = 0; hf < 2; ++hf)
; #pragma unroll
;                     for (int j = 0; j < 4; ++j) wsv[4 * hf + j] = __expf(bl + avv[hf][j] - m_nw);
;                 bf16x8 kt[2];
; #pragma unroll
;                 for (int dd = 0; dd < 2; ++dd) { const u32x2 lo = ktr[dd][k2][0], hi = ktr[dd][k2][1];
;                     u32x4 wv; wv.x = pk2(bflo(lo.x) * wsv[0], bfhi(lo.x) * wsv[1]); wv.y = pk2(bflo(lo.y) * wsv[2], bfhi(lo.y) * wsv[3]);
;                     wv.z = pk2(bflo(hi.x) * wsv[4], bfhi(hi.x) * wsv[5]); wv.w = pk2(bflo(hi.y) * wsv[6], bfhi(hi.y) * wsv[7]); kt[dd] = __builtin_bit_cast(bf16x8, wv); }
; #pragma unroll
;                 for (int et = 0; et < 5; ++et) { const bf16x8 vv = et < 4 ? vf[et] : onesf;
;                     stC[0][et] = mfma16(vv, kt[0], stC[0][et]); stC[1][et] = mfma16(vv, kt[1], stC[1][et]); }
;             }
;         }
;         if (c + 1 < 32) { const bf16_t* qrow = qU + (size_t)(sbn * 1024 + ql);
; #pragma unroll
;             for (int ks = 0; ks < 8; ++ks) qf[ks] = *(const bf16x8*)(qrow + ks * 32); }
	v_mfma_f32_16x16x32_bf16 v[106:109], v[146:149], v[140:143], v[106:109]
	v_mfma_f32_16x16x32_bf16 v[98:101], v[146:149], v[128:131], v[98:101]
	ds_read_b128 v[146:149], v192 offset:8192
	s_waitcnt lgkmcnt(0)
	v_mfma_f32_16x16x32_bf16 v[102:105], v[146:149], v[140:143], v[102:105]
	v_mfma_f32_16x16x32_bf16 v[90:93], v[146:149], v[128:131], v[90:93]
	ds_read_b128 v[146:149], v192 offset:12288
	s_waitcnt lgkmcnt(0)
	v_mfma_f32_16x16x32_bf16 v[94:97], v[146:149], v[140:143], v[94:97]
	v_mfma_f32_16x16x32_bf16 v[82:85], v[146:149], v[128:131], v[82:85]
	v_mfma_f32_16x16x32_bf16 v[86:89], v[0:3], v[140:143], v[86:89]
	ds_read_b128 v[140:143], v190 offset:43904
	s_waitcnt lgkmcnt(0)
	v_add_f32_e32 v134, v189, v140
	v_mfma_f32_16x16x32_bf16 v[78:81], v[0:3], v[128:131], v[78:81]
	ds_read_b128 v[126:129], v191
	ds_read_b128 v[130:133], v190 offset:43968
	v_add_f32_e32 v140, v189, v142
	v_add_f32_e32 v138, v189, v141
	v_add_f32_e32 v141, v189, v143
	v_sub_f32_e32 v134, v134, v139
	s_waitcnt lgkmcnt(0)
	v_add_f32_e32 v130, v189, v130
	v_sub_f32_e32 v130, v130, v139
	v_mul_f32_e32 v130, 0x3fb8aa3b, v130
	v_exp_f32_e32 v142, v130
	v_add_f32_e32 v130, v189, v131
	v_sub_f32_e32 v130, v130, v139
	v_mul_f32_e32 v130, 0x3fb8aa3b, v130
	v_exp_f32_e32 v143, v130
	v_add_f32_e32 v130, v189, v132
	v_sub_f32_e32 v138, v138, v139
	v_sub_f32_e32 v130, v130, v139
	v_mul_f32_e32 v134, 0x3fb8aa3b, v134
	v_mul_f32_e32 v138, 0x3fb8aa3b, v138
	v_mul_f32_e32 v130, 0x3fb8aa3b, v130
	v_exp_f32_e32 v134, v134
	v_exp_f32_e32 v138, v138
	v_sub_f32_e32 v140, v140, v139
	v_exp_f32_e32 v146, v130
	v_add_f32_e32 v130, v189, v133
	v_mul_f32_e32 v140, 0x3fb8aa3b, v140
	v_sub_f32_e32 v141, v141, v139
	v_sub_f32_e32 v130, v130, v139
	v_exp_f32_e32 v140, v140
	v_mul_f32_e32 v141, 0x3fb8aa3b, v141
	v_mul_f32_e32 v130, 0x3fb8aa3b, v130
	v_exp_f32_e32 v141, v141
	v_exp_f32_e32 v139, v130
	v_lshlrev_b32_e32 v130, 16, v124
	v_and_b32_e32 v124, 0xffff0000, v124
	v_mul_f32_e32 v130, v134, v130
	v_mul_f32_e32 v124, v138, v124
	v_cvt_pk_bf16_f32 v130, v130, v124
	v_lshlrev_b32_e32 v124, 16, v125
	v_mul_f32_e32 v124, v140, v124
	v_and_b32_e32 v125, 0xffff0000, v125
	v_mul_f32_e32 v125, v141, v125
	v_cvt_pk_bf16_f32 v131, v124, v125
	v_lshlrev_b32_e32 v124, 16, v120
	v_and_b32_e32 v120, 0xffff0000, v120
	v_mul_f32_e32 v120, v143, v120
	v_mul_f32_e32 v124, v142, v124
	v_cvt_pk_bf16_f32 v132, v124, v120
	v_lshlrev_b32_e32 v120, 16, v121
	v_and_b32_e32 v121, 0xffff0000, v121
	v_mul_f32_e32 v120, v146, v120
	v_mul_f32_e32 v121, v139, v121
	v_cvt_pk_bf16_f32 v133, v120, v121
	v_lshlrev_b32_e32 v120, 16, v122
	v_and_b32_e32 v121, 0xffff0000, v122
	v_mul_f32_e32 v120, v134, v120
	v_mul_f32_e32 v121, v138, v121
	v_cvt_pk_bf16_f32 v120, v120, v121
	v_lshlrev_b32_e32 v121, 16, v123
	v_and_b32_e32 v122, 0xffff0000, v123
	v_mul_f32_e32 v121, v140, v121
	v_mul_f32_e32 v122, v141, v122
	v_cvt_pk_bf16_f32 v121, v121, v122
	v_lshlrev_b32_e32 v122, 16, v118
	v_and_b32_e32 v118, 0xffff0000, v118
	v_mul_f32_e32 v122, v142, v122
	v_mul_f32_e32 v118, v143, v118
	v_cvt_pk_bf16_f32 v122, v122, v118
	v_lshlrev_b32_e32 v118, 16, v119
	v_and_b32_e32 v119, 0xffff0000, v119
	v_mul_f32_e32 v118, v146, v118
	v_mfma_f32_16x16x32_bf16 v[114:117], v[126:129], v[130:133], v[114:117]
	v_mul_f32_e32 v119, v139, v119
	v_cvt_pk_bf16_f32 v123, v118, v119
	s_nop 0
	v_mfma_f32_16x16x32_bf16 v[110:113], v[126:129], v[120:123], v[110:113]
	ds_read_b128 v[124:127], v191 offset:4096
	s_waitcnt lgkmcnt(0)
	v_mfma_f32_16x16x32_bf16 v[106:109], v[124:127], v[130:133], v[106:109]
	v_mfma_f32_16x16x32_bf16 v[98:101], v[124:127], v[120:123], v[98:101]
	ds_read_b128 v[124:127], v191 offset:8192
	s_waitcnt lgkmcnt(0)
	v_mfma_f32_16x16x32_bf16 v[102:105], v[124:127], v[130:133], v[102:105]
	v_mfma_f32_16x16x32_bf16 v[90:93], v[124:127], v[120:123], v[90:93]
	ds_read_b128 v[124:127], v191 offset:12288
	s_waitcnt lgkmcnt(0)
	v_mfma_f32_16x16x32_bf16 v[94:97], v[124:127], v[130:133], v[94:97]
	v_mfma_f32_16x16x32_bf16 v[82:85], v[124:127], v[120:123], v[82:85]
	v_mfma_f32_16x16x32_bf16 v[86:89], v[0:3], v[130:133], v[86:89]
	v_mfma_f32_16x16x32_bf16 v[78:81], v[0:3], v[120:123], v[78:81]
	s_branch .LBB0_305
